# norm layer 0: pos[row] load hoisted above the next-row prefetch with counted vmcnt so the prefetch stays in flight
# speedup vs baseline: 1.0238x; 1.0072x over previous
.LBB0_397:
	v_add_u32_e32 v74, 8, v74
	v_cmp_gt_i32_e32 vcc, s88, v74
	v_cmp_le_i32_e64 s[4:5], s88, v74
	s_and_b64 s[6:7], exec, s[24:25]
	s_cbranch_scc0 .Lnorm_nopos
	global_load_dword v32, v[78:79], off
.Lnorm_nopos:
	s_and_saveexec_b64 s[0:1], vcc
	s_cbranch_execz .LBB0_399
	global_load_dwordx4 v[42:45], v[86:87], off offset:-4096 nt
	global_load_dwordx4 v[38:41], v[86:87], off offset:-3072 nt
	global_load_dwordx4 v[34:37], v[86:87], off offset:-2048 nt
	global_load_dwordx4 v[28:31], v[86:87], off offset:-1024 nt
	global_load_dwordx4 v[24:27], v[86:87], off nt
	global_load_dwordx4 v[20:23], v[86:87], off offset:1024 nt
	global_load_dwordx4 v[16:19], v[86:87], off offset:2048 nt
	global_load_dwordx4 v[12:15], v[86:87], off offset:3072 nt
.LBB0_399:
	s_or_b64 exec, exec, s[0:1]
	s_andn2_b64 vcc, exec, s[24:25]
	s_mov_b64 s[14:15], 0x1000
	s_cbranch_vccnz .LBB0_396
	s_brev_b32 s0, 18
	s_and_b64 s[6:7], s[4:5], exec
	s_cbranch_scc1 .Lnorm_w0
	s_waitcnt vmcnt(8)
	s_branch .Lnorm_w1

.Lnorm_w1:
	v_cvt_f32_i32_e32 v75, v32
	v_mul_f32_e32 v97, v88, v75
	v_and_b32_e32 v98, 0x7fffffff, v97
	v_cmp_nlt_f32_e64 s[0:1], |v97|, s0
	s_and_saveexec_b64 s[6:7], s[0:1]
	s_xor_b64 s[12:13], exec, s[6:7]
	s_cbranch_execz .LBB0_402
	v_lshrrev_b32_e32 v32, 23, v98
	v_add_u32_e32 v32, 0xffffff88, v32
	v_cmp_lt_u32_e32 vcc, 63, v32
	s_mov_b32 s8, 0xfe5163ab
	s_nop 0
	v_cndmask_b32_e32 v99, 0, v223, vcc
	v_add_u32_e32 v32, v99, v32
	v_cmp_lt_u32_e64 s[0:1], 31, v32
	s_nop 1
	v_cndmask_b32_e64 v99, 0, v224, s[0:1]
	v_add_u32_e32 v32, v99, v32
	v_cmp_lt_u32_e64 s[6:7], 31, v32
	s_nop 1
	v_cndmask_b32_e64 v99, 0, v224, s[6:7]
	v_add_u32_e32 v99, v99, v32
	v_and_b32_e32 v32, 0x7fffff, v98
	v_or_b32_e32 v112, 0x800000, v32
	v_mad_u64_u32 v[100:101], s[8:9], v112, s8, 0
	v_mov_b32_e32 v32, v101
	s_mov_b32 s8, 0x3c439041
	v_mad_u64_u32 v[102:103], s[8:9], v112, s8, v[32:33]
	v_mov_b32_e32 v32, v103
	s_mov_b32 s8, 0xdb629599
	v_mad_u64_u32 v[104:105], s[8:9], v112, s8, v[32:33]
	v_mov_b32_e32 v32, v105
	s_mov_b32 s8, 0xf534ddc0
	v_mad_u64_u32 v[106:107], s[8:9], v112, s8, v[32:33]
	v_mov_b32_e32 v32, v107
	s_mov_b32 s8, 0xfc2757d1
	v_mad_u64_u32 v[108:109], s[8:9], v112, s8, v[32:33]
	v_mov_b32_e32 v32, v109
	s_mov_b32 s8, 0x4e441529
	v_mad_u64_u32 v[110:111], s[8:9], v112, s8, v[32:33]
	v_mov_b32_e32 v32, v111
	s_mov_b32 s8, 0xa2f9836e
	v_mad_u64_u32 v[112:113], s[8:9], v112, s8, v[32:33]
	v_cndmask_b32_e32 v101, v110, v106, vcc
	v_cndmask_b32_e32 v32, v112, v108, vcc
	v_cndmask_b32_e32 v105, v113, v110, vcc
	v_cndmask_b32_e64 v103, v32, v101, s[0:1]
	v_cndmask_b32_e64 v32, v105, v32, s[0:1]
	v_cndmask_b32_e32 v105, v108, v104, vcc
	v_cndmask_b32_e64 v101, v101, v105, s[0:1]
	v_cndmask_b32_e64 v32, v32, v103, s[6:7]
	v_cndmask_b32_e64 v103, v103, v101, s[6:7]
	v_sub_u32_e32 v107, 32, v99
	v_alignbit_b32 v108, v32, v103, v107
	v_cmp_eq_u32_e64 s[8:9], 0, v99
	v_cndmask_b32_e32 v100, v104, v100, vcc
	s_nop 0
	v_cndmask_b32_e64 v99, v108, v32, s[8:9]
	v_cndmask_b32_e32 v32, v106, v102, vcc
	v_cndmask_b32_e64 v102, v105, v32, s[0:1]
	v_cndmask_b32_e64 v101, v101, v102, s[6:7]
	v_alignbit_b32 v105, v103, v101, v107
	v_cndmask_b32_e64 v103, v105, v103, s[8:9]
	v_bfe_u32 v108, v99, 29, 1
	v_cndmask_b32_e64 v32, v32, v100, s[0:1]
	v_alignbit_b32 v105, v99, v103, 30
	v_sub_u32_e32 v109, 0, v108
	v_cndmask_b32_e64 v32, v102, v32, s[6:7]
	v_xor_b32_e32 v105, v105, v109
	v_alignbit_b32 v100, v101, v32, v107
	v_cndmask_b32_e64 v100, v100, v101, s[8:9]
	v_ffbh_u32_e32 v102, v105
	v_alignbit_b32 v101, v103, v100, 30
	v_min_u32_e32 v102, 32, v102
	v_alignbit_b32 v32, v100, v32, 30
	v_xor_b32_e32 v101, v101, v109
	v_sub_u32_e32 v103, 31, v102
	v_xor_b32_e32 v32, v32, v109
	v_alignbit_b32 v104, v105, v101, v103
	v_alignbit_b32 v32, v101, v32, v103
	v_alignbit_b32 v100, v104, v32, 9
	v_ffbh_u32_e32 v101, v100
	v_min_u32_e32 v101, 32, v101
	v_lshrrev_b32_e32 v106, 29, v99
	v_not_b32_e32 v103, v101
	v_alignbit_b32 v32, v100, v32, v103
	v_lshlrev_b32_e32 v100, 31, v106
	v_or_b32_e32 v103, 0x33000000, v100
	v_add_lshl_u32 v101, v101, v102, 23
	v_lshrrev_b32_e32 v32, 9, v32
	v_sub_u32_e32 v101, v103, v101
	v_or_b32_e32 v100, 0.5, v100
	v_lshlrev_b32_e32 v102, 23, v102
	v_or_b32_e32 v32, v101, v32
	v_lshrrev_b32_e32 v101, 9, v104
	v_sub_u32_e32 v100, v100, v102
	v_or_b32_e32 v100, v101, v100
	v_mul_f32_e32 v101, 0x3fc90fda, v100
	s_mov_b32 s0, 0x3fc90fda
	v_fma_f32 v102, v100, s0, -v101
	v_fmac_f32_e32 v102, 0x33a22168, v100
	v_fmac_f32_e32 v102, 0x3fc90fda, v32
	v_lshrrev_b32_e32 v99, 30, v99
	v_add_f32_e32 v32, v101, v102
	v_add_u32_e32 v99, v108, v99
